# grid barrier spin loops: sleep removed so release detection is one poll round trip
# speedup vs baseline: 1.0015x; 1.0015x over previous
; __device__ __forceinline__ unsigned xb_ld(unsigned* p)              { return __hip_atomic_load(p, __ATOMIC_RELAXED, __HIP_MEMORY_SCOPE_AGENT); }
; #define XB_SPIN(cond, bar) do { unsigned _sp = 0; while (cond) { __builtin_amdgcn_s_sleep(1); \
;     if ((++_sp & 255u) == 0u) { if (xb_ld(&(bar)[XB_TMO])) break; if (_sp > XB_SPIN_CAP) { atomicAdd(&(bar)[XB_TMO], 1u); break; } } } } while (0)
; __device__ __forceinline__ void xcd_barrier(const XcdBarrier& b) {
;     ...
;             XB_SPIN(xb_ld(&bar[XB_XGEN(b.x)]) == gen, bar);
.LBB0_40:
	s_and_b32 s3, s2, 0xff
	s_mov_b64 s[18:19], -1
	s_cmp_lg_u32 s3, 0
	s_mov_b64 s[22:23], -1
	s_nop 0
	s_cbranch_scc0 .LBB0_43
	s_and_b64 vcc, exec, s[22:23]
	s_cbranch_vccz .LBB0_39

; __device__ __forceinline__ unsigned xb_ld(unsigned* p)              { return __hip_atomic_load(p, __ATOMIC_RELAXED, __HIP_MEMORY_SCOPE_AGENT); }
; #define XB_SPIN(cond, bar) do { unsigned _sp = 0; while (cond) { __builtin_amdgcn_s_sleep(1); \
;     if ((++_sp & 255u) == 0u) { if (xb_ld(&(bar)[XB_TMO])) break; if (_sp > XB_SPIN_CAP) { atomicAdd(&(bar)[XB_TMO], 1u); break; } } } } while (0)
; __device__ __forceinline__ void xcd_barrier(const XcdBarrier& b) {
;     ...
;             else XB_SPIN(xb_ld(&bar[XB_TOPGEN]) == tg, bar);
.LBB0_57:
	s_and_b32 s3, s2, 0xff
	s_mov_b64 s[16:17], -1
	s_cmp_lg_u32 s3, 0
	s_mov_b64 s[20:21], -1
	s_nop 0
	s_cbranch_scc0 .LBB0_60
	s_and_b64 vcc, exec, s[20:21]
	s_cbranch_vccz .LBB0_56
